# adds: bpermute lane indices for softmax max exchange computed with 3 ops instead of 10
# baseline (speedup 1.0000x reference)
; __device__ __forceinline__ void attn_item(LAS unsigned char* lds, const bf16_t* z, const float* kmean, bf16_t* cat, int b, int h, int j) {
;     ...
;                 float mx = fmaxf(fmaxf(s[0][qg][0], s[0][qg][1]), fmaxf(s[0][qg][2], s[0][qg][3]));
; #pragma unroll
;                 for (int ks = 1; ks < 4; ++ks) mx = fmaxf(mx, fmaxf(fmaxf(s[ks][qg][0], s[ks][qg][1]), fmaxf(s[ks][qg][2], s[ks][qg][3])));
;                 mx = fmaxf(mx, __shfl_xor(mx, 16)); mx = fmaxf(mx, __shfl_xor(mx, 32));
;                 mx = selq ? mx : -1e30f;
;                 const float mnew = fmaxf(mrun[qg], mx); const float alpha = __builtin_amdgcn_exp2f((mrun[qg] - mnew) * SC); mrun[qg] = mnew;
;                 const float sub = selq ? (-mnew * SC) : -INFINITY;
.LBB0_1599:
	v_mbcnt_hi_u32_b32 v114, -1, v227
	v_lshlrev_b32_e32 v143, 2, v114
	v_xor_b32_e32 v142, 64, v143
	v_xor_b32_e32 v143, 0x80, v143
	s_and_b64 s[2:3], s[36:37], exec
	s_cselect_b32 s2, s49, s83
	s_lshl_b32 s2, 1, s2
	v_and_b32_e32 v114, s2, v106
	v_cmp_ne_u32_e32 vcc, 0, v114
	v_max3_f32 v114, v82, v83, v84
	v_max3_f32 v144, v85, v86, v87
	v_max3_f32 v145, v88, v89, v90
	v_max3_f32 v146, v91, v92, v93
	v_max3_f32 v114, v114, v94, v95
	v_max3_f32 v144, v144, v96, v97
	v_max3_f32 v114, v114, v144, v145
	v_max_f32_e32 v114, v114, v146
	ds_bpermute_b32 v144, v142, v114
	s_or_b64 s[10:11], s[36:37], vcc
	s_waitcnt lgkmcnt(0)
	v_max_f32_e32 v114, v114, v144
	ds_bpermute_b32 v144, v143, v114
	s_waitcnt lgkmcnt(0)
	v_max_f32_e32 v114, v114, v144
	v_cndmask_b32_e64 v114, v194, v114, s[10:11]
	v_max_f32_e32 v114, v110, v114
	v_sub_f32_e32 v110, v110, v114
	v_mul_f32_e32 v110, 0x3e38aa3b, v110
	v_exp_f32_e32 v110, v110
	s_nop 0
	v_cmp_neq_f32_e32 vcc, 1.0, v110
	s_cbranch_vccz .LBB0_1601
	v_pk_mul_f32 v[6:7], v[6:7], v[110:111] op_sel_hi:[1,0]
	v_pk_mul_f32 v[4:5], v[4:5], v[110:111] op_sel_hi:[1,0]
	v_pk_mul_f32 v[32:33], v[32:33], v[110:111] op_sel_hi:[1,0]
	v_pk_mul_f32 v[30:31], v[30:31], v[110:111] op_sel_hi:[1,0]
	v_pk_mul_f32 v[40:41], v[40:41], v[110:111] op_sel_hi:[1,0]
	v_pk_mul_f32 v[38:39], v[38:39], v[110:111] op_sel_hi:[1,0]
	v_pk_mul_f32 v[48:49], v[48:49], v[110:111] op_sel_hi:[1,0]
	v_pk_mul_f32 v[46:47], v[46:47], v[110:111] op_sel_hi:[1,0]
